# attention tile prologue: the 8 Q loads are issued before the second entry barrier instead of after it
# speedup vs baseline: 1.0005x; 1.0005x over previous
.LBB0_1429:
	v_mov_b32_e32 v4, v252
	s_waitcnt vmcnt(63) expcnt(7) lgkmcnt(15)
	v_readfirstlane_b32 s4, v4
	s_barrier
	s_ashr_i32 s10, s4, 6
	v_and_b32_e32 v173, 63, v4
	s_mul_i32 s5, s10, 0x410
	s_add_i32 s8, s5, 0
	s_add_i32 s11, s18, 0xffb9
	s_and_b32 s9, s11, 0xffff
	s_mul_i32 s2, s9, 0x8889
	s_lshr_b32 s2, s2, 22
	s_lshl_b32 s3, s2, 7
	s_mulk_i32 s2, 0x78
	s_sub_i32 s2, s11, s2
	s_add_i32 s2, s2, 8
	s_and_b32 s2, s2, 0xffff
	s_add_i32 s33, s3, s2
	s_lshr_b32 s2, s33, 7
	s_lshl_b32 s76, s2, 22
	s_lshl_b32 s2, s2, 3
	s_and_b32 s6, s4, 0xffffffc0
	s_add_i32 s2, s10, s2
	s_ashr_i32 s7, s6, 31
	s_ashr_i32 s3, s2, 31
	s_lshl_b64 s[2:3], s[2:3], 20
	s_lshl_b64 s[4:5], s[6:7], 1
	v_lshrrev_b32_e32 v5, 5, v173
	s_add_u32 s30, s95, s4
	v_and_b32_e32 v172, 31, v4
	s_addc_u32 s31, s22, s5
	v_lshlrev_b32_e32 v0, 4, v5
	v_lshl_add_u64 v[2:3], s[30:31], 0, v[0:1]
	v_lshl_or_b32 v0, s33, 6, v172
	v_lshlrev_b64 v[6:7], 10, v[0:1]
	v_or_b32_e32 v162, 32, v0
	v_mov_b32_e32 v163, v1
	v_lshl_add_u64 v[18:19], v[2:3], 0, v[6:7]
	v_lshlrev_b64 v[6:7], 10, v[162:163]
	v_lshl_add_u64 v[2:3], v[2:3], 0, v[6:7]
	global_load_dwordx4 v[6:9], v[18:19], off
	global_load_dwordx4 v[10:13], v[18:19], off offset:32
	global_load_dwordx4 v[14:17], v[18:19], off offset:64
	s_nop 0
	global_load_dwordx4 v[18:21], v[18:19], off offset:96
	s_nop 0
	global_load_dwordx4 v[22:25], v[2:3], off
	global_load_dwordx4 v[26:29], v[2:3], off offset:32
	global_load_dwordx4 v[30:33], v[2:3], off offset:64
	global_load_dwordx4 v[34:37], v[2:3], off offset:96
	s_waitcnt lgkmcnt(0)
	s_barrier
	s_mulk_i32 s10, 0x1bf0
	v_lshlrev_b32_e32 v38, 4, v173
	s_add_i32 s10, s8, s10
	v_and_b32_e32 v3, 32, v4
	v_add_u32_e32 v174, s10, v38
	s_lshl_b32 s10, s11, 16
	v_lshlrev_b32_e32 v2, 10, v172
	v_lshrrev_b32_e32 v3, 1, v3
	v_or3_b32 v2, s10, v2, v3
	s_lshl_b64 s[10:11], s[76:77], 1
	s_add_u32 s10, s10, s4
	v_mov_b32_e32 v3, v1
	s_addc_u32 s11, s11, s5
	v_lshl_add_u64 v[2:3], s[10:11], 0, v[2:3]
	s_mul_hi_u32 s10, s9, 0x2222223
	s_mul_hi_u32 s11, s10, 0x780000
	s_mul_i32 s30, s10, 0x780000
	v_subrev_co_u32_e32 v166, vcc, s30, v2
	v_mov_b32_e32 v2, s11
	s_lshl_b32 s9, s9, 13
	v_subb_co_u32_e32 v167, vcc, v3, v2, vcc
	s_add_u32 s2, s2, s9
	v_lshlrev_b32_e32 v2, 4, v172
	v_lshlrev_b32_e32 v3, 10, v5
	v_or3_b32 v2, v3, v2, s2
	s_addc_u32 s3, s3, 0
	v_or_b32_e32 v3, 0x200, v2
	s_mul_i32 s10, s10, 0xf0000
	v_mov_b32_e32 v4, s3
	v_subrev_co_u32_e32 v168, vcc, s10, v3
	v_lshlrev_b32_e32 v165, 2, v5
	s_nop 0
	v_subbrev_co_u32_e32 v169, vcc, 0, v4, vcc
	v_subrev_co_u32_e32 v170, vcc, s10, v2
	v_sub_u32_e32 v2, v172, v165
	s_nop 0
	v_subbrev_co_u32_e32 v171, vcc, 0, v4, vcc
	v_add_u32_e32 v177, 0x220, v2
	v_mov_b32_e32 v2, v1
	v_mov_b32_e32 v3, v1
	v_mov_b32_e32 v4, v1
	v_mov_b32_e32 v5, v1
	v_mov_b32_e32 v175, 0
	v_mov_b32_e32 v189, 0xf149f2ca
	s_mov_b32 s9, -1
	v_mov_b32_e32 v199, 0xf149f2ca
	v_mov_b32_e32 v176, 0
	v_readfirstlane_b32 s98, v252
	v_mbcnt_lo_u32_b32 v249, -1, 0
	v_mbcnt_hi_u32_b32 v249, -1, v249
	s_lshr_b32 s101, s98, 6
	s_lshl_b32 s98, s101, 13
	s_add_i32 s98, s98, 0x14000
	s_add_i32 s99, s98, 0x1c00
	s_mov_b32 s100, 0x1000
	s_cmp_eq_u32 s101, 7
	s_cselect_b32 s99, 0x3000, s99
	s_cselect_b32 s100, 0xfffe0400, s100
	s_cmp_ge_u32 s101, 4
	s_cselect_b32 s32, 4, 0x63
	v_and_b32_e32 v246, 31, v249
	v_lshrrev_b32_e32 v247, 5, v249
	v_bfe_u32 v248, v249, 1, 3
	v_lshl_add_u32 v250, v246, 7, s98
	v_xor_b32_e32 v241, v247, v248
	v_lshl_add_u32 v241, v241, 4, v250
	v_or_b32_e32 v242, 2, v247
	v_xor_b32_e32 v242, v242, v248
	v_lshl_add_u32 v242, v242, 4, v250
	v_or_b32_e32 v243, 4, v247
	v_xor_b32_e32 v243, v243, v248
	v_lshl_add_u32 v243, v243, 4, v250
	v_or_b32_e32 v244, 6, v247
	v_xor_b32_e32 v244, v244, v248
	v_lshl_add_u32 v244, v244, 4, v250
	v_mov_b32_e32 v245, 0x1000
	v_mov_b32_e32 v251, s100
	v_cmp_lt_u32_e32 vcc, 23, v246
	s_nop 1
	v_cndmask_b32_e32 v245, v245, v251, vcc
	v_add_u32_e32 v248, v244, v245
	v_add_u32_e32 v247, v243, v245
	v_add_u32_e32 v246, v242, v245
	v_add_u32_e32 v245, v241, v245
	v_lshrrev_b32_e32 v250, 3, v249
	v_lshlrev_b32_e32 v250, 10, v250
	v_and_b32_e32 v251, 7, v249
	v_lshrrev_b32_e32 v142, 4, v249
	v_xor_b32_e32 v251, v251, v142
	v_lshl_add_u32 v142, v251, 4, v250
	v_xor_b32_e32 v251, 4, v251
	v_lshl_add_u32 v250, v251, 4, v250
	v_add_u32_e32 v250, 0x2000, v250
	v_readfirstlane_b32 s100, v166
	v_readfirstlane_b32 s101, v167
	s_nop 0
	s_add_u32 s100, s100, s86
	s_addc_u32 s101, s101, s87
	s_add_u32 s100, s100, 0x85ee200
	s_addc_u32 s101, s101, 0
	v_mov_b32_e32 v143, 0
	v_mov_b32_e32 v251, 0
	v_lshl_add_u64 v[166:167], s[100:101], 0, v[142:143]
	v_lshl_add_u64 v[250:251], s[100:101], 0, v[250:251]
	s_mov_b64 s[100:101], 0x4000
	s_mov_b32 m0, s98
	s_nop 0
	global_load_lds_dwordx4 v[166:167], off
	s_add_i32 m0, s98, 0x400
	s_nop 0
	global_load_lds_dwordx4 v[250:251], off
	v_lshl_add_u64 v[142:143], v[166:167], 0, s[100:101]
	s_add_i32 m0, s98, 0x800
	s_nop 0
	global_load_lds_dwordx4 v[142:143], off
	v_lshl_add_u64 v[144:145], v[250:251], 0, s[100:101]
	s_add_i32 m0, s98, 0xc00
	s_nop 0
	global_load_lds_dwordx4 v[144:145], off
	v_lshl_add_u64 v[142:143], v[142:143], 0, s[100:101]
	s_add_i32 m0, s98, 0x1000
	s_nop 0
	global_load_lds_dwordx4 v[142:143], off
	v_lshl_add_u64 v[144:145], v[144:145], 0, s[100:101]
	s_add_i32 m0, s98, 0x1400
	s_nop 0
	global_load_lds_dwordx4 v[144:145], off
	v_lshl_add_u64 v[142:143], v[142:143], 0, s[100:101]
	s_add_i32 m0, s98, 0x1800
	s_nop 0
	global_load_lds_dwordx4 v[142:143], off
	v_lshl_add_u64 v[144:145], v[144:145], 0, s[100:101]
	s_mov_b32 m0, s99
	s_nop 0
	global_load_lds_dwordx4 v[144:145], off
	s_load_dwordx2 s[2:3], s[0:1], 0x40
	s_sub_i32 s10, s98, 0x14000
	s_lshr_b32 s10, s10, 13
	s_mul_i32 s10, s10, 0x101
	v_add_u32_e32 v44, s10, v173
	v_ashrrev_i32_e32 v45, 31, v44
	v_lshl_add_u32 v43, v173, 2, s8
	s_waitcnt lgkmcnt(0)
	v_lshl_add_u64 v[44:45], v[44:45], 2, s[2:3]
	global_load_dword v38, v[44:45], off
	global_load_dword v39, v[44:45], off offset:256
	global_load_dword v40, v[44:45], off offset:512
	global_load_dword v41, v[44:45], off offset:768
	v_cmp_eq_u32_e32 vcc, 0, v173
	s_and_saveexec_b64 s[2:3], vcc
	global_load_dword v42, v[44:45], off offset:1024
	s_waitcnt vmcnt(0)
	v_mul_f32_e32 v42, 0x3fb8aa3b, v42
	ds_write_b32 v43, v42 offset:1024
	ds_write_b32 v43, v42 offset:1028
	ds_write_b32 v43, v42 offset:1032
	ds_write_b32 v43, v42 offset:1036
	s_or_b64 exec, exec, s[2:3]
	v_mul_f32_e32 v38, 0x3fb8aa3b, v38
	v_mul_f32_e32 v39, 0x3fb8aa3b, v39
	v_mul_f32_e32 v40, 0x3fb8aa3b, v40
	v_mul_f32_e32 v41, 0x3fb8aa3b, v41
	ds_write_b32 v43, v38
	ds_write_b32 v43, v39 offset:256
	ds_write_b32 v43, v40 offset:512
	ds_write_b32 v43, v41 offset:768
	s_waitcnt vmcnt(7)
	s_waitcnt vmcnt(6)
	s_waitcnt vmcnt(5)
	s_waitcnt vmcnt(4)
	s_waitcnt vmcnt(3)
	s_waitcnt vmcnt(2)
	s_waitcnt vmcnt(1)
	s_waitcnt vmcnt(0)
	ds_write_b128 v174, v[6:9] offset:16384
	ds_write_b128 v174, v[10:13] offset:17408
	ds_write_b128 v174, v[14:17] offset:18432
	ds_write_b128 v174, v[18:21] offset:19456
	ds_write_b128 v174, v[22:25] offset:20480
	ds_write_b128 v174, v[26:29] offset:21504
	ds_write_b128 v174, v[30:33] offset:22528
	ds_write_b128 v174, v[34:37] offset:23552
	v_mov_b32_e32 v16, v1
	v_mov_b32_e32 v17, v1
	v_mov_b32_e32 v6, v1
	v_mov_b32_e32 v7, v1
	v_mov_b32_e32 v8, v1
	v_mov_b32_e32 v9, v1
	v_mov_b32_e32 v10, v1
	v_mov_b32_e32 v11, v1
	v_mov_b32_e32 v12, v1
	v_mov_b32_e32 v13, v1
	v_mov_b32_e32 v14, v1
	v_mov_b32_e32 v15, v1
	v_mov_b64_e32 v[48:49], v[16:17]
	v_mov_b64_e32 v[32:33], v[16:17]
	v_mov_b64_e32 v[64:65], v[16:17]
	v_mov_b64_e32 v[46:47], v[14:15]
	v_mov_b64_e32 v[44:45], v[12:13]
	v_mov_b64_e32 v[42:43], v[10:11]
	v_mov_b64_e32 v[40:41], v[8:9]
	v_mov_b64_e32 v[38:39], v[6:7]
	v_mov_b64_e32 v[36:37], v[4:5]
	v_mov_b64_e32 v[34:35], v[2:3]
	v_mov_b64_e32 v[30:31], v[14:15]
	v_mov_b64_e32 v[28:29], v[12:13]
	v_mov_b64_e32 v[26:27], v[10:11]
	v_mov_b64_e32 v[24:25], v[8:9]
	v_mov_b64_e32 v[22:23], v[6:7]
	v_mov_b64_e32 v[20:21], v[4:5]
	v_mov_b64_e32 v[18:19], v[2:3]
	v_mov_b64_e32 v[62:63], v[14:15]
	v_mov_b64_e32 v[60:61], v[12:13]
	v_mov_b64_e32 v[58:59], v[10:11]
	v_mov_b64_e32 v[56:57], v[8:9]
	v_mov_b64_e32 v[54:55], v[6:7]
	v_mov_b64_e32 v[52:53], v[4:5]
	v_mov_b64_e32 v[50:51], v[2:3]
	v_mov_b32_e32 v216, 0x3e38aa3b
	v_mov_b32_e32 v217, 0x3e38aa3b
	v_xor_b32_e32 v249, 32, v179
	v_lshlrev_b32_e32 v249, 2, v249
